# prologue compress-bias (pe@W1+b1, f32) spread over 32 waves with 4-way k split per wave and a 2-batch-ahead load ring instead of 128 dependent round trips on 8 waves
# speedup vs baseline: 1.0176x; 1.0016x over previous
.LBB0_1240:
	s_or_b64 exec, exec, s[20:21]
	s_cmp_lt_i32 s80, 4
	s_cselect_b64 s[0:1], -1, 0
	s_and_saveexec_b64 s[4:5], s[0:1]
	s_cbranch_execz .LBB0_1244
	v_readfirstlane_b32 s2, v166
	s_lshr_b32 s2, s2, 6
	s_lshl_b32 s3, s80, 3
	s_add_i32 s2, s2, s3
	s_lshr_b32 s3, s2, 4
	s_and_b32 s2, s2, 15
	s_lshl_b32 s2, s2, 4
	v_and_b32_e32 v2, 15, v222
	v_add_u32_e32 v2, s2, v2
	v_lshrrev_b32_e32 v3, 4, v222
	s_lshl_b32 s6, s3, 8
	v_add_u32_e32 v36, s6, v2
	v_lshlrev_b32_e32 v36, 2, v36
	v_readlane_b32 s8, v253, 22
	v_readlane_b32 s9, v253, 23
	v_readlane_b32 s0, v253, 13
	v_readlane_b32 s1, v253, 30
	s_sub_u32 s0, s0, 0x3c00
	s_subb_u32 s1, s1, 0
	s_lshl_b32 s6, s3, 21
	s_add_u32 s0, s0, s6
	s_addc_u32 s1, s1, 0
	v_lshlrev_b32_e32 v34, 19, v3
	v_lshl_add_u32 v34, v2, 2, v34
	v_mov_b32_e32 v35, 0
	global_load_dword v33, v36, s[8:9]
	v_lshl_add_u64 v[22:23], v[34:35], 0, s[0:1]
	s_mov_b64 s[20:21], 0x1000
	v_lshl_add_u64 v[24:25], v[22:23], 0, s[20:21]
	v_lshl_add_u64 v[26:27], v[24:25], 0, s[20:21]
	v_lshl_add_u64 v[28:29], v[26:27], 0, s[20:21]
	s_mov_b64 s[20:21], 0x4000
	v_readlane_b32 s0, v253, 18
	v_readlane_b32 s1, v253, 19
	s_lshl_b32 s6, s3, 13
	s_add_u32 s0, s0, s6
	s_addc_u32 s1, s1, 0
	v_lshlrev_b32_e32 v34, 11, v3
	v_lshl_add_u64 v[30:31], v[34:35], 0, s[0:1]
	s_mov_b64 s[10:11], 64
	v_mov_b32_e32 v0, 0
	s_mov_b32 s6, 7
	global_load_dword v40, v[22:23], off
	global_load_dword v41, v[22:23], off offset:1024
	global_load_dword v42, v[22:23], off offset:2048
	global_load_dword v43, v[22:23], off offset:3072
	global_load_dword v44, v[24:25], off
	global_load_dword v45, v[24:25], off offset:1024
	global_load_dword v46, v[24:25], off offset:2048
	global_load_dword v47, v[24:25], off offset:3072
	global_load_dword v48, v[26:27], off
	global_load_dword v49, v[26:27], off offset:1024
	global_load_dword v50, v[26:27], off offset:2048
	global_load_dword v51, v[26:27], off offset:3072
	global_load_dword v52, v[28:29], off
	global_load_dword v53, v[28:29], off offset:1024
	global_load_dword v54, v[28:29], off offset:2048
	global_load_dword v55, v[28:29], off offset:3072
	global_load_dwordx4 v[104:107], v[30:31], off
	global_load_dwordx4 v[108:111], v[30:31], off offset:16
	global_load_dwordx4 v[112:115], v[30:31], off offset:32
	global_load_dwordx4 v[116:119], v[30:31], off offset:48
	v_lshl_add_u64 v[22:23], v[22:23], 0, s[20:21]
	v_lshl_add_u64 v[24:25], v[24:25], 0, s[20:21]
	v_lshl_add_u64 v[26:27], v[26:27], 0, s[20:21]
	v_lshl_add_u64 v[28:29], v[28:29], 0, s[20:21]
	v_lshl_add_u64 v[30:31], v[30:31], 0, s[10:11]
	global_load_dword v56, v[22:23], off
	global_load_dword v57, v[22:23], off offset:1024
	global_load_dword v58, v[22:23], off offset:2048
	global_load_dword v59, v[22:23], off offset:3072
	global_load_dword v60, v[24:25], off
	global_load_dword v61, v[24:25], off offset:1024
	global_load_dword v62, v[24:25], off offset:2048
	global_load_dword v63, v[24:25], off offset:3072
	global_load_dword v64, v[26:27], off
	global_load_dword v65, v[26:27], off offset:1024
	global_load_dword v66, v[26:27], off offset:2048
	global_load_dword v67, v[26:27], off offset:3072
	global_load_dword v68, v[28:29], off
	global_load_dword v69, v[28:29], off offset:1024
	global_load_dword v70, v[28:29], off offset:2048
	global_load_dword v71, v[28:29], off offset:3072
	global_load_dwordx4 v[120:123], v[30:31], off
	global_load_dwordx4 v[124:127], v[30:31], off offset:16
	global_load_dwordx4 v[128:131], v[30:31], off offset:32
	global_load_dwordx4 v[132:135], v[30:31], off offset:48
	v_lshl_add_u64 v[22:23], v[22:23], 0, s[20:21]
	v_lshl_add_u64 v[24:25], v[24:25], 0, s[20:21]
	v_lshl_add_u64 v[26:27], v[26:27], 0, s[20:21]
	v_lshl_add_u64 v[28:29], v[28:29], 0, s[20:21]
	v_lshl_add_u64 v[30:31], v[30:31], 0, s[10:11]
.Lcbias_loop:
	global_load_dword v72, v[22:23], off
	global_load_dword v73, v[22:23], off offset:1024
	global_load_dword v74, v[22:23], off offset:2048
	global_load_dword v75, v[22:23], off offset:3072
	global_load_dword v76, v[24:25], off
	global_load_dword v77, v[24:25], off offset:1024
	global_load_dword v78, v[24:25], off offset:2048
	global_load_dword v79, v[24:25], off offset:3072
	global_load_dword v80, v[26:27], off
	global_load_dword v81, v[26:27], off offset:1024
	global_load_dword v82, v[26:27], off offset:2048
	global_load_dword v83, v[26:27], off offset:3072
	global_load_dword v84, v[28:29], off
	global_load_dword v85, v[28:29], off offset:1024
	global_load_dword v86, v[28:29], off offset:2048
	global_load_dword v87, v[28:29], off offset:3072
	global_load_dwordx4 v[136:139], v[30:31], off
	global_load_dwordx4 v[140:143], v[30:31], off offset:16
	global_load_dwordx4 v[144:147], v[30:31], off offset:32
	global_load_dwordx4 v[148:151], v[30:31], off offset:48
	v_lshl_add_u64 v[22:23], v[22:23], 0, s[20:21]
	v_lshl_add_u64 v[24:25], v[24:25], 0, s[20:21]
	v_lshl_add_u64 v[26:27], v[26:27], 0, s[20:21]
	v_lshl_add_u64 v[28:29], v[28:29], 0, s[20:21]
	v_lshl_add_u64 v[30:31], v[30:31], 0, s[10:11]
	s_waitcnt vmcnt(40)
	v_fmac_f32_e32 v0, v104, v40
	v_fmac_f32_e32 v0, v105, v41
	v_fmac_f32_e32 v0, v106, v42
	v_fmac_f32_e32 v0, v107, v43
	v_fmac_f32_e32 v0, v108, v44
	v_fmac_f32_e32 v0, v109, v45
	v_fmac_f32_e32 v0, v110, v46
	v_fmac_f32_e32 v0, v111, v47
	v_fmac_f32_e32 v0, v112, v48
	v_fmac_f32_e32 v0, v113, v49
	v_fmac_f32_e32 v0, v114, v50
	v_fmac_f32_e32 v0, v115, v51
	v_fmac_f32_e32 v0, v116, v52
	v_fmac_f32_e32 v0, v117, v53
	v_fmac_f32_e32 v0, v118, v54
	v_fmac_f32_e32 v0, v119, v55
	global_load_dword v88, v[22:23], off
	global_load_dword v89, v[22:23], off offset:1024
	global_load_dword v90, v[22:23], off offset:2048
	global_load_dword v91, v[22:23], off offset:3072
	global_load_dword v92, v[24:25], off
	global_load_dword v93, v[24:25], off offset:1024
	global_load_dword v94, v[24:25], off offset:2048
	global_load_dword v95, v[24:25], off offset:3072
	global_load_dword v96, v[26:27], off
	global_load_dword v97, v[26:27], off offset:1024
	global_load_dword v98, v[26:27], off offset:2048
	global_load_dword v99, v[26:27], off offset:3072
	global_load_dword v100, v[28:29], off
	global_load_dword v101, v[28:29], off offset:1024
	global_load_dword v102, v[28:29], off offset:2048
	global_load_dword v103, v[28:29], off offset:3072
	global_load_dwordx4 v[6:9], v[30:31], off
	global_load_dwordx4 v[10:13], v[30:31], off offset:16
	global_load_dwordx4 v[14:17], v[30:31], off offset:32
	global_load_dwordx4 v[18:21], v[30:31], off offset:48
	v_lshl_add_u64 v[22:23], v[22:23], 0, s[20:21]
	v_lshl_add_u64 v[24:25], v[24:25], 0, s[20:21]
	v_lshl_add_u64 v[26:27], v[26:27], 0, s[20:21]
	v_lshl_add_u64 v[28:29], v[28:29], 0, s[20:21]
	v_lshl_add_u64 v[30:31], v[30:31], 0, s[10:11]
	s_waitcnt vmcnt(40)
	v_fmac_f32_e32 v0, v120, v56
	v_fmac_f32_e32 v0, v121, v57
	v_fmac_f32_e32 v0, v122, v58
	v_fmac_f32_e32 v0, v123, v59
	v_fmac_f32_e32 v0, v124, v60
	v_fmac_f32_e32 v0, v125, v61
	v_fmac_f32_e32 v0, v126, v62
	v_fmac_f32_e32 v0, v127, v63
	v_fmac_f32_e32 v0, v128, v64
	v_fmac_f32_e32 v0, v129, v65
	v_fmac_f32_e32 v0, v130, v66
	v_fmac_f32_e32 v0, v131, v67
	v_fmac_f32_e32 v0, v132, v68
	v_fmac_f32_e32 v0, v133, v69
	v_fmac_f32_e32 v0, v134, v70
	v_fmac_f32_e32 v0, v135, v71
	global_load_dword v40, v[22:23], off
	global_load_dword v41, v[22:23], off offset:1024
	global_load_dword v42, v[22:23], off offset:2048
	global_load_dword v43, v[22:23], off offset:3072
	global_load_dword v44, v[24:25], off
	global_load_dword v45, v[24:25], off offset:1024
	global_load_dword v46, v[24:25], off offset:2048
	global_load_dword v47, v[24:25], off offset:3072
	global_load_dword v48, v[26:27], off
	global_load_dword v49, v[26:27], off offset:1024
	global_load_dword v50, v[26:27], off offset:2048
	global_load_dword v51, v[26:27], off offset:3072
	global_load_dword v52, v[28:29], off
	global_load_dword v53, v[28:29], off offset:1024
	global_load_dword v54, v[28:29], off offset:2048
	global_load_dword v55, v[28:29], off offset:3072
	global_load_dwordx4 v[104:107], v[30:31], off
	global_load_dwordx4 v[108:111], v[30:31], off offset:16
	global_load_dwordx4 v[112:115], v[30:31], off offset:32
	global_load_dwordx4 v[116:119], v[30:31], off offset:48
	v_lshl_add_u64 v[22:23], v[22:23], 0, s[20:21]
	v_lshl_add_u64 v[24:25], v[24:25], 0, s[20:21]
	v_lshl_add_u64 v[26:27], v[26:27], 0, s[20:21]
	v_lshl_add_u64 v[28:29], v[28:29], 0, s[20:21]
	v_lshl_add_u64 v[30:31], v[30:31], 0, s[10:11]
	s_waitcnt vmcnt(40)
	v_fmac_f32_e32 v0, v136, v72
	v_fmac_f32_e32 v0, v137, v73
	v_fmac_f32_e32 v0, v138, v74
	v_fmac_f32_e32 v0, v139, v75
	v_fmac_f32_e32 v0, v140, v76
	v_fmac_f32_e32 v0, v141, v77
	v_fmac_f32_e32 v0, v142, v78
	v_fmac_f32_e32 v0, v143, v79
	v_fmac_f32_e32 v0, v144, v80
	v_fmac_f32_e32 v0, v145, v81
	v_fmac_f32_e32 v0, v146, v82
	v_fmac_f32_e32 v0, v147, v83
	v_fmac_f32_e32 v0, v148, v84
	v_fmac_f32_e32 v0, v149, v85
	v_fmac_f32_e32 v0, v150, v86
	v_fmac_f32_e32 v0, v151, v87
	global_load_dword v56, v[22:23], off
	global_load_dword v57, v[22:23], off offset:1024
	global_load_dword v58, v[22:23], off offset:2048
	global_load_dword v59, v[22:23], off offset:3072
	global_load_dword v60, v[24:25], off
	global_load_dword v61, v[24:25], off offset:1024
	global_load_dword v62, v[24:25], off offset:2048
	global_load_dword v63, v[24:25], off offset:3072
	global_load_dword v64, v[26:27], off
	global_load_dword v65, v[26:27], off offset:1024
	global_load_dword v66, v[26:27], off offset:2048
	global_load_dword v67, v[26:27], off offset:3072
	global_load_dword v68, v[28:29], off
	global_load_dword v69, v[28:29], off offset:1024
	global_load_dword v70, v[28:29], off offset:2048
	global_load_dword v71, v[28:29], off offset:3072
	global_load_dwordx4 v[120:123], v[30:31], off
	global_load_dwordx4 v[124:127], v[30:31], off offset:16
	global_load_dwordx4 v[128:131], v[30:31], off offset:32
	global_load_dwordx4 v[132:135], v[30:31], off offset:48
	v_lshl_add_u64 v[22:23], v[22:23], 0, s[20:21]
	v_lshl_add_u64 v[24:25], v[24:25], 0, s[20:21]
	v_lshl_add_u64 v[26:27], v[26:27], 0, s[20:21]
	v_lshl_add_u64 v[28:29], v[28:29], 0, s[20:21]
	v_lshl_add_u64 v[30:31], v[30:31], 0, s[10:11]
	s_waitcnt vmcnt(40)
	v_fmac_f32_e32 v0, v6, v88
	v_fmac_f32_e32 v0, v7, v89
	v_fmac_f32_e32 v0, v8, v90
	v_fmac_f32_e32 v0, v9, v91
	v_fmac_f32_e32 v0, v10, v92
	v_fmac_f32_e32 v0, v11, v93
	v_fmac_f32_e32 v0, v12, v94
	v_fmac_f32_e32 v0, v13, v95
	v_fmac_f32_e32 v0, v14, v96
	v_fmac_f32_e32 v0, v15, v97
	v_fmac_f32_e32 v0, v16, v98
	v_fmac_f32_e32 v0, v17, v99
	v_fmac_f32_e32 v0, v18, v100
	v_fmac_f32_e32 v0, v19, v101
	v_fmac_f32_e32 v0, v20, v102
	v_fmac_f32_e32 v0, v21, v103
	s_sub_u32 s6, s6, 1
	s_cmp_lg_u32 s6, 0
	s_cbranch_scc1 .Lcbias_loop
	global_load_dword v72, v[22:23], off
	global_load_dword v73, v[22:23], off offset:1024
	global_load_dword v74, v[22:23], off offset:2048
	global_load_dword v75, v[22:23], off offset:3072
	global_load_dword v76, v[24:25], off
	global_load_dword v77, v[24:25], off offset:1024
	global_load_dword v78, v[24:25], off offset:2048
	global_load_dword v79, v[24:25], off offset:3072
	global_load_dword v80, v[26:27], off
	global_load_dword v81, v[26:27], off offset:1024
	global_load_dword v82, v[26:27], off offset:2048
	global_load_dword v83, v[26:27], off offset:3072
	global_load_dword v84, v[28:29], off
	global_load_dword v85, v[28:29], off offset:1024
	global_load_dword v86, v[28:29], off offset:2048
	global_load_dword v87, v[28:29], off offset:3072
	global_load_dwordx4 v[136:139], v[30:31], off
	global_load_dwordx4 v[140:143], v[30:31], off offset:16
	global_load_dwordx4 v[144:147], v[30:31], off offset:32
	global_load_dwordx4 v[148:151], v[30:31], off offset:48
	v_lshl_add_u64 v[22:23], v[22:23], 0, s[20:21]
	v_lshl_add_u64 v[24:25], v[24:25], 0, s[20:21]
	v_lshl_add_u64 v[26:27], v[26:27], 0, s[20:21]
	v_lshl_add_u64 v[28:29], v[28:29], 0, s[20:21]
	v_lshl_add_u64 v[30:31], v[30:31], 0, s[10:11]
	s_waitcnt vmcnt(40)
	v_fmac_f32_e32 v0, v104, v40
	v_fmac_f32_e32 v0, v105, v41
	v_fmac_f32_e32 v0, v106, v42
	v_fmac_f32_e32 v0, v107, v43
	v_fmac_f32_e32 v0, v108, v44
	v_fmac_f32_e32 v0, v109, v45
	v_fmac_f32_e32 v0, v110, v46
	v_fmac_f32_e32 v0, v111, v47
	v_fmac_f32_e32 v0, v112, v48
	v_fmac_f32_e32 v0, v113, v49
	v_fmac_f32_e32 v0, v114, v50
	v_fmac_f32_e32 v0, v115, v51
	v_fmac_f32_e32 v0, v116, v52
	v_fmac_f32_e32 v0, v117, v53
	v_fmac_f32_e32 v0, v118, v54
	v_fmac_f32_e32 v0, v119, v55
	global_load_dword v88, v[22:23], off
	global_load_dword v89, v[22:23], off offset:1024
	global_load_dword v90, v[22:23], off offset:2048
	global_load_dword v91, v[22:23], off offset:3072
	global_load_dword v92, v[24:25], off
	global_load_dword v93, v[24:25], off offset:1024
	global_load_dword v94, v[24:25], off offset:2048
	global_load_dword v95, v[24:25], off offset:3072
	global_load_dword v96, v[26:27], off
	global_load_dword v97, v[26:27], off offset:1024
	global_load_dword v98, v[26:27], off offset:2048
	global_load_dword v99, v[26:27], off offset:3072
	global_load_dword v100, v[28:29], off
	global_load_dword v101, v[28:29], off offset:1024
	global_load_dword v102, v[28:29], off offset:2048
	global_load_dword v103, v[28:29], off offset:3072
	global_load_dwordx4 v[6:9], v[30:31], off
	global_load_dwordx4 v[10:13], v[30:31], off offset:16
	global_load_dwordx4 v[14:17], v[30:31], off offset:32
	global_load_dwordx4 v[18:21], v[30:31], off offset:48
	v_lshl_add_u64 v[22:23], v[22:23], 0, s[20:21]
	v_lshl_add_u64 v[24:25], v[24:25], 0, s[20:21]
	v_lshl_add_u64 v[26:27], v[26:27], 0, s[20:21]
	v_lshl_add_u64 v[28:29], v[28:29], 0, s[20:21]
	v_lshl_add_u64 v[30:31], v[30:31], 0, s[10:11]
	s_waitcnt vmcnt(40)
	v_fmac_f32_e32 v0, v120, v56
	v_fmac_f32_e32 v0, v121, v57
	v_fmac_f32_e32 v0, v122, v58
	v_fmac_f32_e32 v0, v123, v59
	v_fmac_f32_e32 v0, v124, v60
	v_fmac_f32_e32 v0, v125, v61
	v_fmac_f32_e32 v0, v126, v62
	v_fmac_f32_e32 v0, v127, v63
	v_fmac_f32_e32 v0, v128, v64
	v_fmac_f32_e32 v0, v129, v65
	v_fmac_f32_e32 v0, v130, v66
	v_fmac_f32_e32 v0, v131, v67
	v_fmac_f32_e32 v0, v132, v68
	v_fmac_f32_e32 v0, v133, v69
	v_fmac_f32_e32 v0, v134, v70
	v_fmac_f32_e32 v0, v135, v71
	s_waitcnt vmcnt(20)
	v_fmac_f32_e32 v0, v136, v72
	v_fmac_f32_e32 v0, v137, v73
	v_fmac_f32_e32 v0, v138, v74
	v_fmac_f32_e32 v0, v139, v75
	v_fmac_f32_e32 v0, v140, v76
	v_fmac_f32_e32 v0, v141, v77
	v_fmac_f32_e32 v0, v142, v78
	v_fmac_f32_e32 v0, v143, v79
	v_fmac_f32_e32 v0, v144, v80
	v_fmac_f32_e32 v0, v145, v81
	v_fmac_f32_e32 v0, v146, v82
	v_fmac_f32_e32 v0, v147, v83
	v_fmac_f32_e32 v0, v148, v84
	v_fmac_f32_e32 v0, v149, v85
	v_fmac_f32_e32 v0, v150, v86
	v_fmac_f32_e32 v0, v151, v87
	s_waitcnt vmcnt(0)
	v_fmac_f32_e32 v0, v6, v88
	v_fmac_f32_e32 v0, v7, v89
	v_fmac_f32_e32 v0, v8, v90
	v_fmac_f32_e32 v0, v9, v91
	v_fmac_f32_e32 v0, v10, v92
	v_fmac_f32_e32 v0, v11, v93
	v_fmac_f32_e32 v0, v12, v94
	v_fmac_f32_e32 v0, v13, v95
	v_fmac_f32_e32 v0, v14, v96
	v_fmac_f32_e32 v0, v15, v97
	v_fmac_f32_e32 v0, v16, v98
	v_fmac_f32_e32 v0, v17, v99
	v_fmac_f32_e32 v0, v18, v100
	v_fmac_f32_e32 v0, v19, v101
	v_fmac_f32_e32 v0, v20, v102
	v_fmac_f32_e32 v0, v21, v103
	v_mov_b32_e32 v32, v0
	s_nop 1
	v_permlane32_swap_b32_e32 v32, v0
	s_nop 1
	v_add_f32_e32 v0, v32, v0
	v_mov_b32_e32 v32, v0
	s_nop 1
	v_permlane16_swap_b32_e32 v32, v0
	s_nop 1
	v_add_f32_e32 v0, v32, v0
	v_add_f32_e32 v0, v0, v33
	v_readlane_b32 s0, v254, 29
	v_readlane_b32 s1, v254, 30
	s_mov_b64 exec, 0xffff
	s_nop 4
	global_store_dword v36, v0, s[0:1]
